# removed all s_setprio (GEMM per-phase flips and scan block); otherwise as previous
# baseline (speedup 1.0000x reference)
.LBB0_495:
	s_and_b64 vcc, exec, s[4:5]
	s_cbranch_vccz .LBB0_484
	ds_read_b128 v[100:103], v97 offset:0
	ds_read_b128 v[108:111], v97 offset:16384
	ds_read_b128 v[112:115], v97 offset:24576
	ds_read_b128 v[104:107], v97 offset:8192
	ds_read_b128 v[116:119], v97 offset:32768
	ds_read_b128 v[180:183], v1 offset:40960
	ds_read_b128 v[120:123], v97 offset:256
	ds_read_b128 v[128:131], v97 offset:16640
	ds_read_b128 v[132:135], v97 offset:24832
	ds_read_b128 v[124:127], v97 offset:8448
	ds_read_b128 v[136:139], v97 offset:33024
	v_lshl_add_u32 v224, v61, 6, v98
	s_waitcnt lgkmcnt(6)
	v_pk_mul_f32 v[140:141], v[82:83], v[100:101]
	v_pk_mul_f32 v[142:143], v[82:83], v[108:109]
	v_pk_mul_f32 v[144:145], v[80:81], v[110:111]
	v_pk_fma_f32 v[140:141], v[80:81], v[102:103], v[140:141]
	s_waitcnt lgkmcnt(5)
	v_pk_fma_f32 v[142:143], v[180:181], v[112:113], v[142:143] op_sel_hi:[0,1,1]
	v_pk_fma_f32 v[144:145], v[180:181], v[114:115], v[144:145] op_sel_hi:[0,1,1]
	v_add_f32_e32 v148, v140, v141
	ds_read_b128 v[160:163], v97 offset:512
	s_nop 0
	v_add_f32_dpp v148, v148, v148 quad_perm:[1,0,3,2] row_mask:0xf bank_mask:0xf bound_ctrl:1
	ds_read_b128 v[168:171], v97 offset:16896
	s_nop 0
	v_add_f32_dpp v148, v148, v148 quad_perm:[2,3,0,1] row_mask:0xf bank_mask:0xf bound_ctrl:1
	ds_read_b128 v[172:175], v97 offset:25088
	ds_read_b128 v[164:167], v97 offset:8704
	v_add_f32_dpp v148, v148, v148 row_ror:4 row_mask:0xf bank_mask:0xf bound_ctrl:1
	ds_read_b128 v[176:179], v97 offset:33280
	s_nop 0
	v_add_f32_dpp v148, v148, v148 row_ror:8 row_mask:0xf bank_mask:0xf bound_ctrl:1
	v_pk_fma_f32 v[82:83], v[104:105], v[148:149], v[142:143] op_sel_hi:[1,0,1]
	v_pk_fma_f32 v[80:81], v[106:107], v[148:149], v[144:145] op_sel_hi:[1,0,1]
	s_waitcnt lgkmcnt(5)
	v_pk_mul_f32 v[140:141], v[82:83], v[120:121]
	v_pk_mul_f32 v[142:143], v[82:83], v[128:129]
	v_pk_mul_f32 v[144:145], v[80:81], v[130:131]
	v_pk_fma_f32 v[140:141], v[80:81], v[122:123], v[140:141]
	v_pk_fma_f32 v[142:143], v[180:181], v[132:133], v[142:143] op_sel:[1,0,0]
	v_pk_fma_f32 v[144:145], v[180:181], v[134:135], v[144:145] op_sel:[1,0,0]
	v_add_f32_e32 v148, v140, v141
	v_pk_mul_f32 v[146:147], v[116:117], v[82:83]
	ds_read_b128 v[100:103], v97 offset:768
	v_add_f32_dpp v148, v148, v148 quad_perm:[1,0,3,2] row_mask:0xf bank_mask:0xf bound_ctrl:1
	v_pk_fma_f32 v[146:147], v[118:119], v[80:81], v[146:147]
	ds_read_b128 v[108:111], v97 offset:17152
	v_add_f32_dpp v148, v148, v148 quad_perm:[2,3,0,1] row_mask:0xf bank_mask:0xf bound_ctrl:1
	ds_read_b128 v[112:115], v97 offset:25344
	ds_read_b128 v[104:107], v97 offset:8960
	v_add_f32_dpp v148, v148, v148 row_ror:4 row_mask:0xf bank_mask:0xf bound_ctrl:1
	ds_read_b128 v[116:119], v97 offset:33536
	v_add_f32_e32 v188, v146, v147
	v_add_f32_dpp v148, v148, v148 row_ror:8 row_mask:0xf bank_mask:0xf bound_ctrl:1
	v_pk_fma_f32 v[82:83], v[124:125], v[148:149], v[142:143] op_sel_hi:[1,0,1]
	v_pk_fma_f32 v[80:81], v[126:127], v[148:149], v[144:145] op_sel_hi:[1,0,1]
	s_waitcnt lgkmcnt(5)
	v_pk_mul_f32 v[140:141], v[82:83], v[160:161]
	v_pk_mul_f32 v[142:143], v[82:83], v[168:169]
	v_pk_mul_f32 v[144:145], v[80:81], v[170:171]
	v_pk_fma_f32 v[140:141], v[80:81], v[162:163], v[140:141]
	v_pk_fma_f32 v[142:143], v[182:183], v[172:173], v[142:143] op_sel_hi:[0,1,1]
	v_pk_fma_f32 v[144:145], v[182:183], v[174:175], v[144:145] op_sel_hi:[0,1,1]
	v_add_f32_e32 v148, v140, v141
	v_pk_mul_f32 v[146:147], v[136:137], v[82:83]
	ds_read_b128 v[120:123], v97 offset:1024
	v_add_f32_dpp v148, v148, v148 quad_perm:[1,0,3,2] row_mask:0xf bank_mask:0xf bound_ctrl:1
	v_pk_fma_f32 v[146:147], v[138:139], v[80:81], v[146:147]
	ds_read_b128 v[128:131], v97 offset:17408
	v_add_f32_dpp v148, v148, v148 quad_perm:[2,3,0,1] row_mask:0xf bank_mask:0xf bound_ctrl:1
	ds_read_b128 v[132:135], v97 offset:25600
	ds_read_b128 v[124:127], v97 offset:9216
	v_add_f32_dpp v148, v148, v148 row_ror:4 row_mask:0xf bank_mask:0xf bound_ctrl:1
	ds_read_b128 v[136:139], v97 offset:33792
	v_add_f32_e32 v189, v146, v147
	v_add_f32_dpp v148, v148, v148 row_ror:8 row_mask:0xf bank_mask:0xf bound_ctrl:1
	ds_read_b128 v[184:187], v1 offset:40976
	v_pk_fma_f32 v[82:83], v[164:165], v[148:149], v[142:143] op_sel_hi:[1,0,1]
	v_pk_fma_f32 v[80:81], v[166:167], v[148:149], v[144:145] op_sel_hi:[1,0,1]
	s_waitcnt lgkmcnt(6)
	v_pk_mul_f32 v[140:141], v[82:83], v[100:101]
	v_pk_mul_f32 v[142:143], v[82:83], v[108:109]
	v_pk_mul_f32 v[144:145], v[80:81], v[110:111]
	v_pk_fma_f32 v[140:141], v[80:81], v[102:103], v[140:141]
	v_pk_fma_f32 v[142:143], v[182:183], v[112:113], v[142:143] op_sel:[1,0,0]
	v_pk_fma_f32 v[144:145], v[182:183], v[114:115], v[144:145] op_sel:[1,0,0]
	v_add_f32_e32 v148, v140, v141
	v_pk_mul_f32 v[146:147], v[176:177], v[82:83]
	ds_read_b128 v[160:163], v97 offset:1280
	v_add_f32_dpp v148, v148, v148 quad_perm:[1,0,3,2] row_mask:0xf bank_mask:0xf bound_ctrl:1
	v_pk_fma_f32 v[146:147], v[178:179], v[80:81], v[146:147]
	ds_read_b128 v[168:171], v97 offset:17664
	v_add_f32_dpp v148, v148, v148 quad_perm:[2,3,0,1] row_mask:0xf bank_mask:0xf bound_ctrl:1
	ds_read_b128 v[172:175], v97 offset:25856
	ds_read_b128 v[164:167], v97 offset:9472
	v_add_f32_dpp v148, v148, v148 row_ror:4 row_mask:0xf bank_mask:0xf bound_ctrl:1
	ds_read_b128 v[176:179], v97 offset:34048
	v_add_f32_e32 v190, v146, v147
	v_add_f32_dpp v148, v148, v148 row_ror:8 row_mask:0xf bank_mask:0xf bound_ctrl:1
	v_pk_fma_f32 v[82:83], v[104:105], v[148:149], v[142:143] op_sel_hi:[1,0,1]
	v_pk_fma_f32 v[80:81], v[106:107], v[148:149], v[144:145] op_sel_hi:[1,0,1]
	s_waitcnt lgkmcnt(6)
	v_pk_mul_f32 v[140:141], v[82:83], v[120:121]
	v_pk_mul_f32 v[142:143], v[82:83], v[128:129]
	v_pk_mul_f32 v[144:145], v[80:81], v[130:131]
	v_pk_fma_f32 v[140:141], v[80:81], v[122:123], v[140:141]
	s_waitcnt lgkmcnt(5)
	v_pk_fma_f32 v[142:143], v[184:185], v[132:133], v[142:143] op_sel_hi:[0,1,1]
	v_pk_fma_f32 v[144:145], v[184:185], v[134:135], v[144:145] op_sel_hi:[0,1,1]
	v_add_f32_e32 v148, v140, v141
	v_pk_mul_f32 v[146:147], v[116:117], v[82:83]
	ds_read_b128 v[100:103], v97 offset:1536
	v_add_f32_dpp v148, v148, v148 quad_perm:[1,0,3,2] row_mask:0xf bank_mask:0xf bound_ctrl:1
	v_pk_fma_f32 v[146:147], v[118:119], v[80:81], v[146:147]
	ds_read_b128 v[108:111], v97 offset:17920
	v_add_f32_dpp v148, v148, v148 quad_perm:[2,3,0,1] row_mask:0xf bank_mask:0xf bound_ctrl:1
	ds_read_b128 v[112:115], v97 offset:26112
	ds_read_b128 v[104:107], v97 offset:9728
	v_add_f32_dpp v148, v148, v148 row_ror:4 row_mask:0xf bank_mask:0xf bound_ctrl:1
	ds_read_b128 v[116:119], v97 offset:34304
	v_add_f32_e32 v191, v146, v147
	v_add_f32_dpp v148, v148, v148 row_ror:8 row_mask:0xf bank_mask:0xf bound_ctrl:1
	v_pk_fma_f32 v[82:83], v[124:125], v[148:149], v[142:143] op_sel_hi:[1,0,1]
	v_pk_fma_f32 v[80:81], v[126:127], v[148:149], v[144:145] op_sel_hi:[1,0,1]
	s_waitcnt lgkmcnt(5)
	v_pk_mul_f32 v[140:141], v[82:83], v[160:161]
	v_pk_mul_f32 v[142:143], v[82:83], v[168:169]
	v_pk_mul_f32 v[144:145], v[80:81], v[170:171]
	v_pk_fma_f32 v[140:141], v[80:81], v[162:163], v[140:141]
	v_pk_fma_f32 v[142:143], v[184:185], v[172:173], v[142:143] op_sel:[1,0,0]
	v_pk_fma_f32 v[144:145], v[184:185], v[174:175], v[144:145] op_sel:[1,0,0]
	v_add_f32_e32 v148, v140, v141
	v_pk_mul_f32 v[146:147], v[136:137], v[82:83]
	ds_read_b128 v[120:123], v97 offset:1792
	v_add_f32_dpp v148, v148, v148 quad_perm:[1,0,3,2] row_mask:0xf bank_mask:0xf bound_ctrl:1
	v_pk_fma_f32 v[146:147], v[138:139], v[80:81], v[146:147]
	ds_read_b128 v[128:131], v97 offset:18176
	v_add_f32_dpp v148, v148, v148 quad_perm:[2,3,0,1] row_mask:0xf bank_mask:0xf bound_ctrl:1
	ds_read_b128 v[132:135], v97 offset:26368
	ds_read_b128 v[124:127], v97 offset:9984
	v_add_f32_dpp v148, v148, v148 row_ror:4 row_mask:0xf bank_mask:0xf bound_ctrl:1
	ds_read_b128 v[136:139], v97 offset:34560
	v_add_f32_e32 v192, v146, v147
	v_add_f32_dpp v148, v148, v148 row_ror:8 row_mask:0xf bank_mask:0xf bound_ctrl:1
	v_pk_fma_f32 v[82:83], v[164:165], v[148:149], v[142:143] op_sel_hi:[1,0,1]
	v_pk_fma_f32 v[80:81], v[166:167], v[148:149], v[144:145] op_sel_hi:[1,0,1]
	s_waitcnt lgkmcnt(5)
	v_pk_mul_f32 v[140:141], v[82:83], v[100:101]
	v_pk_mul_f32 v[142:143], v[82:83], v[108:109]
	v_pk_mul_f32 v[144:145], v[80:81], v[110:111]
	v_pk_fma_f32 v[140:141], v[80:81], v[102:103], v[140:141]
	v_pk_fma_f32 v[142:143], v[186:187], v[112:113], v[142:143] op_sel_hi:[0,1,1]
	v_pk_fma_f32 v[144:145], v[186:187], v[114:115], v[144:145] op_sel_hi:[0,1,1]
	v_add_f32_e32 v148, v140, v141
	v_pk_mul_f32 v[146:147], v[176:177], v[82:83]
	ds_read_b128 v[160:163], v97 offset:2048
	v_add_f32_dpp v148, v148, v148 quad_perm:[1,0,3,2] row_mask:0xf bank_mask:0xf bound_ctrl:1
	v_pk_fma_f32 v[146:147], v[178:179], v[80:81], v[146:147]
	ds_read_b128 v[168:171], v97 offset:18432
	v_add_f32_dpp v148, v148, v148 quad_perm:[2,3,0,1] row_mask:0xf bank_mask:0xf bound_ctrl:1
	ds_read_b128 v[172:175], v97 offset:26624
	ds_read_b128 v[164:167], v97 offset:10240
	v_add_f32_dpp v148, v148, v148 row_ror:4 row_mask:0xf bank_mask:0xf bound_ctrl:1
	ds_read_b128 v[176:179], v97 offset:34816
	v_add_f32_e32 v193, v146, v147
	v_add_f32_dpp v148, v148, v148 row_ror:8 row_mask:0xf bank_mask:0xf bound_ctrl:1
	ds_read_b128 v[180:183], v1 offset:40992
	v_pk_fma_f32 v[82:83], v[104:105], v[148:149], v[142:143] op_sel_hi:[1,0,1]
	v_pk_fma_f32 v[80:81], v[106:107], v[148:149], v[144:145] op_sel_hi:[1,0,1]
	s_waitcnt lgkmcnt(6)
	v_pk_mul_f32 v[140:141], v[82:83], v[120:121]
	v_pk_mul_f32 v[142:143], v[82:83], v[128:129]
	v_pk_mul_f32 v[144:145], v[80:81], v[130:131]
	v_pk_fma_f32 v[140:141], v[80:81], v[122:123], v[140:141]
	v_pk_fma_f32 v[142:143], v[186:187], v[132:133], v[142:143] op_sel:[1,0,0]
	v_pk_fma_f32 v[144:145], v[186:187], v[134:135], v[144:145] op_sel:[1,0,0]
	v_add_f32_e32 v148, v140, v141
	v_pk_mul_f32 v[146:147], v[116:117], v[82:83]
	ds_read_b128 v[100:103], v97 offset:2304
	v_add_f32_dpp v148, v148, v148 quad_perm:[1,0,3,2] row_mask:0xf bank_mask:0xf bound_ctrl:1
	v_pk_fma_f32 v[146:147], v[118:119], v[80:81], v[146:147]
	ds_read_b128 v[108:111], v97 offset:18688
	v_add_f32_dpp v148, v148, v148 quad_perm:[2,3,0,1] row_mask:0xf bank_mask:0xf bound_ctrl:1
	ds_read_b128 v[112:115], v97 offset:26880
	ds_read_b128 v[104:107], v97 offset:10496
	v_add_f32_dpp v148, v148, v148 row_ror:4 row_mask:0xf bank_mask:0xf bound_ctrl:1
	ds_read_b128 v[116:119], v97 offset:35072
	v_add_f32_e32 v194, v146, v147
	v_add_f32_dpp v148, v148, v148 row_ror:8 row_mask:0xf bank_mask:0xf bound_ctrl:1
	v_pk_fma_f32 v[82:83], v[124:125], v[148:149], v[142:143] op_sel_hi:[1,0,1]
	v_pk_fma_f32 v[80:81], v[126:127], v[148:149], v[144:145] op_sel_hi:[1,0,1]
	s_waitcnt lgkmcnt(6)
	v_pk_mul_f32 v[140:141], v[82:83], v[160:161]
	v_pk_mul_f32 v[142:143], v[82:83], v[168:169]
	v_pk_mul_f32 v[144:145], v[80:81], v[170:171]
	v_pk_fma_f32 v[140:141], v[80:81], v[162:163], v[140:141]
	s_waitcnt lgkmcnt(5)
	v_pk_fma_f32 v[142:143], v[180:181], v[172:173], v[142:143] op_sel_hi:[0,1,1]
	v_pk_fma_f32 v[144:145], v[180:181], v[174:175], v[144:145] op_sel_hi:[0,1,1]
	v_add_f32_e32 v148, v140, v141
	v_pk_mul_f32 v[146:147], v[136:137], v[82:83]
	ds_read_b128 v[120:123], v97 offset:2560
	v_add_f32_dpp v148, v148, v148 quad_perm:[1,0,3,2] row_mask:0xf bank_mask:0xf bound_ctrl:1
	v_pk_fma_f32 v[146:147], v[138:139], v[80:81], v[146:147]
	ds_read_b128 v[128:131], v97 offset:18944
	v_add_f32_dpp v148, v148, v148 quad_perm:[2,3,0,1] row_mask:0xf bank_mask:0xf bound_ctrl:1
	ds_read_b128 v[132:135], v97 offset:27136
	ds_read_b128 v[124:127], v97 offset:10752
	v_add_f32_dpp v148, v148, v148 row_ror:4 row_mask:0xf bank_mask:0xf bound_ctrl:1
	ds_read_b128 v[136:139], v97 offset:35328
	v_add_f32_e32 v195, v146, v147
	v_add_f32_dpp v148, v148, v148 row_ror:8 row_mask:0xf bank_mask:0xf bound_ctrl:1
	v_pk_fma_f32 v[82:83], v[164:165], v[148:149], v[142:143] op_sel_hi:[1,0,1]
	v_pk_fma_f32 v[80:81], v[166:167], v[148:149], v[144:145] op_sel_hi:[1,0,1]
	s_waitcnt lgkmcnt(5)
	v_pk_mul_f32 v[140:141], v[82:83], v[100:101]
	v_pk_mul_f32 v[142:143], v[82:83], v[108:109]
	v_pk_mul_f32 v[144:145], v[80:81], v[110:111]
	v_pk_fma_f32 v[140:141], v[80:81], v[102:103], v[140:141]
	v_pk_fma_f32 v[142:143], v[180:181], v[112:113], v[142:143] op_sel:[1,0,0]
	v_pk_fma_f32 v[144:145], v[180:181], v[114:115], v[144:145] op_sel:[1,0,0]
	v_add_f32_e32 v148, v140, v141
	v_pk_mul_f32 v[146:147], v[176:177], v[82:83]
	ds_read_b128 v[160:163], v97 offset:2816
	v_add_f32_dpp v148, v148, v148 quad_perm:[1,0,3,2] row_mask:0xf bank_mask:0xf bound_ctrl:1
	v_pk_fma_f32 v[146:147], v[178:179], v[80:81], v[146:147]
	ds_read_b128 v[168:171], v97 offset:19200
	v_add_f32_dpp v148, v148, v148 quad_perm:[2,3,0,1] row_mask:0xf bank_mask:0xf bound_ctrl:1
	ds_read_b128 v[172:175], v97 offset:27392
	ds_read_b128 v[164:167], v97 offset:11008
	v_add_f32_dpp v148, v148, v148 row_ror:4 row_mask:0xf bank_mask:0xf bound_ctrl:1
	ds_read_b128 v[176:179], v97 offset:35584
	v_add_f32_e32 v196, v146, v147
	v_add_f32_dpp v148, v148, v148 row_ror:8 row_mask:0xf bank_mask:0xf bound_ctrl:1
	v_pk_fma_f32 v[82:83], v[104:105], v[148:149], v[142:143] op_sel_hi:[1,0,1]
	v_pk_fma_f32 v[80:81], v[106:107], v[148:149], v[144:145] op_sel_hi:[1,0,1]
	s_waitcnt lgkmcnt(5)
	v_pk_mul_f32 v[140:141], v[82:83], v[120:121]
	v_pk_mul_f32 v[142:143], v[82:83], v[128:129]
	v_pk_mul_f32 v[144:145], v[80:81], v[130:131]
	v_pk_fma_f32 v[140:141], v[80:81], v[122:123], v[140:141]
	v_pk_fma_f32 v[142:143], v[182:183], v[132:133], v[142:143] op_sel_hi:[0,1,1]
	v_pk_fma_f32 v[144:145], v[182:183], v[134:135], v[144:145] op_sel_hi:[0,1,1]
	v_add_f32_e32 v148, v140, v141
	v_pk_mul_f32 v[146:147], v[116:117], v[82:83]
	ds_read_b128 v[100:103], v97 offset:3072
	v_add_f32_dpp v148, v148, v148 quad_perm:[1,0,3,2] row_mask:0xf bank_mask:0xf bound_ctrl:1
	v_pk_fma_f32 v[146:147], v[118:119], v[80:81], v[146:147]
	ds_read_b128 v[108:111], v97 offset:19456
	v_add_f32_dpp v148, v148, v148 quad_perm:[2,3,0,1] row_mask:0xf bank_mask:0xf bound_ctrl:1
	ds_read_b128 v[112:115], v97 offset:27648
	ds_read_b128 v[104:107], v97 offset:11264
	v_add_f32_dpp v148, v148, v148 row_ror:4 row_mask:0xf bank_mask:0xf bound_ctrl:1
	ds_read_b128 v[116:119], v97 offset:35840
	v_add_f32_e32 v197, v146, v147
	v_add_f32_dpp v148, v148, v148 row_ror:8 row_mask:0xf bank_mask:0xf bound_ctrl:1
	ds_read_b128 v[184:187], v1 offset:41008
	v_pk_fma_f32 v[82:83], v[124:125], v[148:149], v[142:143] op_sel_hi:[1,0,1]
	v_pk_fma_f32 v[80:81], v[126:127], v[148:149], v[144:145] op_sel_hi:[1,0,1]
	s_waitcnt lgkmcnt(6)
	v_pk_mul_f32 v[140:141], v[82:83], v[160:161]
	v_pk_mul_f32 v[142:143], v[82:83], v[168:169]
	v_pk_mul_f32 v[144:145], v[80:81], v[170:171]
	v_pk_fma_f32 v[140:141], v[80:81], v[162:163], v[140:141]
	v_pk_fma_f32 v[142:143], v[182:183], v[172:173], v[142:143] op_sel:[1,0,0]
	v_pk_fma_f32 v[144:145], v[182:183], v[174:175], v[144:145] op_sel:[1,0,0]
	v_add_f32_e32 v148, v140, v141
	v_pk_mul_f32 v[146:147], v[136:137], v[82:83]
	ds_read_b128 v[120:123], v97 offset:3328
	v_add_f32_dpp v148, v148, v148 quad_perm:[1,0,3,2] row_mask:0xf bank_mask:0xf bound_ctrl:1
	v_pk_fma_f32 v[146:147], v[138:139], v[80:81], v[146:147]
	ds_read_b128 v[128:131], v97 offset:19712
	v_add_f32_dpp v148, v148, v148 quad_perm:[2,3,0,1] row_mask:0xf bank_mask:0xf bound_ctrl:1
	ds_read_b128 v[132:135], v97 offset:27904
	ds_read_b128 v[124:127], v97 offset:11520
	v_add_f32_dpp v148, v148, v148 row_ror:4 row_mask:0xf bank_mask:0xf bound_ctrl:1
	ds_read_b128 v[136:139], v97 offset:36096
	v_add_f32_e32 v198, v146, v147
	v_add_f32_dpp v148, v148, v148 row_ror:8 row_mask:0xf bank_mask:0xf bound_ctrl:1
	v_pk_fma_f32 v[82:83], v[164:165], v[148:149], v[142:143] op_sel_hi:[1,0,1]
	v_pk_fma_f32 v[80:81], v[166:167], v[148:149], v[144:145] op_sel_hi:[1,0,1]
	s_waitcnt lgkmcnt(6)
	v_pk_mul_f32 v[140:141], v[82:83], v[100:101]
	v_pk_mul_f32 v[142:143], v[82:83], v[108:109]
	v_pk_mul_f32 v[144:145], v[80:81], v[110:111]
	v_pk_fma_f32 v[140:141], v[80:81], v[102:103], v[140:141]
	s_waitcnt lgkmcnt(5)
	v_pk_fma_f32 v[142:143], v[184:185], v[112:113], v[142:143] op_sel_hi:[0,1,1]
	v_pk_fma_f32 v[144:145], v[184:185], v[114:115], v[144:145] op_sel_hi:[0,1,1]
	v_add_f32_e32 v148, v140, v141
	v_pk_mul_f32 v[146:147], v[176:177], v[82:83]
	ds_read_b128 v[160:163], v97 offset:3584
	v_add_f32_dpp v148, v148, v148 quad_perm:[1,0,3,2] row_mask:0xf bank_mask:0xf bound_ctrl:1
	v_pk_fma_f32 v[146:147], v[178:179], v[80:81], v[146:147]
	ds_read_b128 v[168:171], v97 offset:19968
	v_add_f32_dpp v148, v148, v148 quad_perm:[2,3,0,1] row_mask:0xf bank_mask:0xf bound_ctrl:1
	ds_read_b128 v[172:175], v97 offset:28160
	ds_read_b128 v[164:167], v97 offset:11776
	v_add_f32_dpp v148, v148, v148 row_ror:4 row_mask:0xf bank_mask:0xf bound_ctrl:1
	ds_read_b128 v[176:179], v97 offset:36352
	v_add_f32_e32 v199, v146, v147
	v_add_f32_dpp v148, v148, v148 row_ror:8 row_mask:0xf bank_mask:0xf bound_ctrl:1
	v_pk_fma_f32 v[82:83], v[104:105], v[148:149], v[142:143] op_sel_hi:[1,0,1]
	v_pk_fma_f32 v[80:81], v[106:107], v[148:149], v[144:145] op_sel_hi:[1,0,1]
	s_waitcnt lgkmcnt(5)
	v_pk_mul_f32 v[140:141], v[82:83], v[120:121]
	v_pk_mul_f32 v[142:143], v[82:83], v[128:129]
	v_pk_mul_f32 v[144:145], v[80:81], v[130:131]
	v_pk_fma_f32 v[140:141], v[80:81], v[122:123], v[140:141]
	v_pk_fma_f32 v[142:143], v[184:185], v[132:133], v[142:143] op_sel:[1,0,0]
	v_pk_fma_f32 v[144:145], v[184:185], v[134:135], v[144:145] op_sel:[1,0,0]
	v_add_f32_e32 v148, v140, v141
	v_pk_mul_f32 v[146:147], v[116:117], v[82:83]
	ds_read_b128 v[100:103], v97 offset:3840
	v_add_f32_dpp v148, v148, v148 quad_perm:[1,0,3,2] row_mask:0xf bank_mask:0xf bound_ctrl:1
	v_pk_fma_f32 v[146:147], v[118:119], v[80:81], v[146:147]
	ds_read_b128 v[108:111], v97 offset:20224
	v_add_f32_dpp v148, v148, v148 quad_perm:[2,3,0,1] row_mask:0xf bank_mask:0xf bound_ctrl:1
	ds_read_b128 v[112:115], v97 offset:28416
	ds_read_b128 v[104:107], v97 offset:12032
	v_add_f32_dpp v148, v148, v148 row_ror:4 row_mask:0xf bank_mask:0xf bound_ctrl:1
	ds_read_b128 v[116:119], v97 offset:36608
	v_add_f32_e32 v200, v146, v147
	v_add_f32_dpp v148, v148, v148 row_ror:8 row_mask:0xf bank_mask:0xf bound_ctrl:1
	v_pk_fma_f32 v[82:83], v[124:125], v[148:149], v[142:143] op_sel_hi:[1,0,1]
	v_pk_fma_f32 v[80:81], v[126:127], v[148:149], v[144:145] op_sel_hi:[1,0,1]
	s_waitcnt lgkmcnt(5)
	v_pk_mul_f32 v[140:141], v[82:83], v[160:161]
	v_pk_mul_f32 v[142:143], v[82:83], v[168:169]
	v_pk_mul_f32 v[144:145], v[80:81], v[170:171]
	v_pk_fma_f32 v[140:141], v[80:81], v[162:163], v[140:141]
	v_pk_fma_f32 v[142:143], v[186:187], v[172:173], v[142:143] op_sel_hi:[0,1,1]
	v_pk_fma_f32 v[144:145], v[186:187], v[174:175], v[144:145] op_sel_hi:[0,1,1]
	v_add_f32_e32 v148, v140, v141
	v_pk_mul_f32 v[146:147], v[136:137], v[82:83]
	ds_read_b128 v[120:123], v97 offset:4096
	v_add_f32_dpp v148, v148, v148 quad_perm:[1,0,3,2] row_mask:0xf bank_mask:0xf bound_ctrl:1
	v_pk_fma_f32 v[146:147], v[138:139], v[80:81], v[146:147]
	ds_read_b128 v[128:131], v97 offset:20480
	v_add_f32_dpp v148, v148, v148 quad_perm:[2,3,0,1] row_mask:0xf bank_mask:0xf bound_ctrl:1
	ds_read_b128 v[132:135], v97 offset:28672
	ds_read_b128 v[124:127], v97 offset:12288
	v_add_f32_dpp v148, v148, v148 row_ror:4 row_mask:0xf bank_mask:0xf bound_ctrl:1
	ds_read_b128 v[136:139], v97 offset:36864
	v_add_f32_e32 v201, v146, v147
	v_add_f32_dpp v148, v148, v148 row_ror:8 row_mask:0xf bank_mask:0xf bound_ctrl:1
	ds_read_b128 v[180:183], v1 offset:41024
	v_pk_fma_f32 v[82:83], v[164:165], v[148:149], v[142:143] op_sel_hi:[1,0,1]
	v_pk_fma_f32 v[80:81], v[166:167], v[148:149], v[144:145] op_sel_hi:[1,0,1]
	s_waitcnt lgkmcnt(6)
	v_pk_mul_f32 v[140:141], v[82:83], v[100:101]
	v_pk_mul_f32 v[142:143], v[82:83], v[108:109]
	v_pk_mul_f32 v[144:145], v[80:81], v[110:111]
	v_pk_fma_f32 v[140:141], v[80:81], v[102:103], v[140:141]
	v_pk_fma_f32 v[142:143], v[186:187], v[112:113], v[142:143] op_sel:[1,0,0]
	v_pk_fma_f32 v[144:145], v[186:187], v[114:115], v[144:145] op_sel:[1,0,0]
	v_add_f32_e32 v148, v140, v141
	v_pk_mul_f32 v[146:147], v[176:177], v[82:83]
	ds_read_b128 v[160:163], v97 offset:4352
	v_add_f32_dpp v148, v148, v148 quad_perm:[1,0,3,2] row_mask:0xf bank_mask:0xf bound_ctrl:1
	v_pk_fma_f32 v[146:147], v[178:179], v[80:81], v[146:147]
	ds_read_b128 v[168:171], v97 offset:20736
	v_add_f32_dpp v148, v148, v148 quad_perm:[2,3,0,1] row_mask:0xf bank_mask:0xf bound_ctrl:1
	ds_read_b128 v[172:175], v97 offset:28928
	ds_read_b128 v[164:167], v97 offset:12544
	v_add_f32_dpp v148, v148, v148 row_ror:4 row_mask:0xf bank_mask:0xf bound_ctrl:1
	ds_read_b128 v[176:179], v97 offset:37120
	v_add_f32_e32 v202, v146, v147
	v_add_f32_dpp v148, v148, v148 row_ror:8 row_mask:0xf bank_mask:0xf bound_ctrl:1
	v_pk_fma_f32 v[82:83], v[104:105], v[148:149], v[142:143] op_sel_hi:[1,0,1]
	v_pk_fma_f32 v[80:81], v[106:107], v[148:149], v[144:145] op_sel_hi:[1,0,1]
	s_waitcnt lgkmcnt(6)
	v_pk_mul_f32 v[140:141], v[82:83], v[120:121]
	v_pk_mul_f32 v[142:143], v[82:83], v[128:129]
	v_pk_mul_f32 v[144:145], v[80:81], v[130:131]
	v_pk_fma_f32 v[140:141], v[80:81], v[122:123], v[140:141]
	s_waitcnt lgkmcnt(5)
	v_pk_fma_f32 v[142:143], v[180:181], v[132:133], v[142:143] op_sel_hi:[0,1,1]
	v_pk_fma_f32 v[144:145], v[180:181], v[134:135], v[144:145] op_sel_hi:[0,1,1]
	v_add_f32_e32 v148, v140, v141
	v_pk_mul_f32 v[146:147], v[116:117], v[82:83]
	ds_read_b128 v[100:103], v97 offset:4608
	v_add_f32_dpp v148, v148, v148 quad_perm:[1,0,3,2] row_mask:0xf bank_mask:0xf bound_ctrl:1
	v_pk_fma_f32 v[146:147], v[118:119], v[80:81], v[146:147]
	ds_read_b128 v[108:111], v97 offset:20992
	v_add_f32_dpp v148, v148, v148 quad_perm:[2,3,0,1] row_mask:0xf bank_mask:0xf bound_ctrl:1
	ds_read_b128 v[112:115], v97 offset:29184
	ds_read_b128 v[104:107], v97 offset:12800
	v_add_f32_dpp v148, v148, v148 row_ror:4 row_mask:0xf bank_mask:0xf bound_ctrl:1
	ds_read_b128 v[116:119], v97 offset:37376
	v_add_f32_e32 v203, v146, v147
	v_add_f32_dpp v148, v148, v148 row_ror:8 row_mask:0xf bank_mask:0xf bound_ctrl:1
	v_pk_fma_f32 v[82:83], v[124:125], v[148:149], v[142:143] op_sel_hi:[1,0,1]
	v_pk_fma_f32 v[80:81], v[126:127], v[148:149], v[144:145] op_sel_hi:[1,0,1]
	s_waitcnt lgkmcnt(5)
	v_pk_mul_f32 v[140:141], v[82:83], v[160:161]
	v_pk_mul_f32 v[142:143], v[82:83], v[168:169]
	v_pk_mul_f32 v[144:145], v[80:81], v[170:171]
	v_pk_fma_f32 v[140:141], v[80:81], v[162:163], v[140:141]
	v_pk_fma_f32 v[142:143], v[180:181], v[172:173], v[142:143] op_sel:[1,0,0]
	v_pk_fma_f32 v[144:145], v[180:181], v[174:175], v[144:145] op_sel:[1,0,0]
	v_add_f32_e32 v148, v140, v141
	v_pk_mul_f32 v[146:147], v[136:137], v[82:83]
	ds_read_b128 v[120:123], v97 offset:4864
	v_add_f32_dpp v148, v148, v148 quad_perm:[1,0,3,2] row_mask:0xf bank_mask:0xf bound_ctrl:1
	v_pk_fma_f32 v[146:147], v[138:139], v[80:81], v[146:147]
	ds_read_b128 v[128:131], v97 offset:21248
	v_add_f32_dpp v148, v148, v148 quad_perm:[2,3,0,1] row_mask:0xf bank_mask:0xf bound_ctrl:1
	ds_read_b128 v[132:135], v97 offset:29440
	ds_read_b128 v[124:127], v97 offset:13056
	v_add_f32_dpp v148, v148, v148 row_ror:4 row_mask:0xf bank_mask:0xf bound_ctrl:1
	ds_read_b128 v[136:139], v97 offset:37632
	v_add_f32_e32 v204, v146, v147
	v_add_f32_dpp v148, v148, v148 row_ror:8 row_mask:0xf bank_mask:0xf bound_ctrl:1
	v_cndmask_b32_e64 v150, v189, v188, s[40:41]
	v_cndmask_b32_e64 v238, v188, v189, s[40:41]
	v_cndmask_b32_e64 v151, v191, v190, s[40:41]
	v_cndmask_b32_e64 v239, v190, v191, s[40:41]
	v_pk_fma_f32 v[82:83], v[164:165], v[148:149], v[142:143] op_sel_hi:[1,0,1]
	v_pk_fma_f32 v[80:81], v[166:167], v[148:149], v[144:145] op_sel_hi:[1,0,1]
	s_waitcnt lgkmcnt(5)
	v_pk_mul_f32 v[140:141], v[82:83], v[100:101]
	v_pk_mul_f32 v[142:143], v[82:83], v[108:109]
	v_pk_mul_f32 v[144:145], v[80:81], v[110:111]
	v_pk_fma_f32 v[140:141], v[80:81], v[102:103], v[140:141]
	v_pk_fma_f32 v[142:143], v[182:183], v[112:113], v[142:143] op_sel_hi:[0,1,1]
	v_pk_fma_f32 v[144:145], v[182:183], v[114:115], v[144:145] op_sel_hi:[0,1,1]
	v_add_f32_e32 v148, v140, v141
	v_pk_mul_f32 v[146:147], v[176:177], v[82:83]
	ds_read_b128 v[160:163], v97 offset:5120
	v_add_f32_dpp v148, v148, v148 quad_perm:[1,0,3,2] row_mask:0xf bank_mask:0xf bound_ctrl:1
	v_pk_fma_f32 v[146:147], v[178:179], v[80:81], v[146:147]
	ds_read_b128 v[168:171], v97 offset:21504
	v_add_f32_dpp v148, v148, v148 quad_perm:[2,3,0,1] row_mask:0xf bank_mask:0xf bound_ctrl:1
	ds_read_b128 v[172:175], v97 offset:29696
	ds_read_b128 v[164:167], v97 offset:13312
	v_add_f32_dpp v148, v148, v148 row_ror:4 row_mask:0xf bank_mask:0xf bound_ctrl:1
	ds_read_b128 v[176:179], v97 offset:37888
	v_add_f32_e32 v205, v146, v147
	v_add_f32_dpp v148, v148, v148 row_ror:8 row_mask:0xf bank_mask:0xf bound_ctrl:1
	ds_read_b128 v[184:187], v1 offset:41040
	v_cndmask_b32_e64 v152, v193, v192, s[40:41]
	v_cndmask_b32_e64 v240, v192, v193, s[40:41]
	v_cndmask_b32_e64 v153, v195, v194, s[40:41]
	v_pk_fma_f32 v[82:83], v[104:105], v[148:149], v[142:143] op_sel_hi:[1,0,1]
	v_pk_fma_f32 v[80:81], v[106:107], v[148:149], v[144:145] op_sel_hi:[1,0,1]
	s_waitcnt lgkmcnt(6)
	v_pk_mul_f32 v[140:141], v[82:83], v[120:121]
	v_pk_mul_f32 v[142:143], v[82:83], v[128:129]
	v_pk_mul_f32 v[144:145], v[80:81], v[130:131]
	v_pk_fma_f32 v[140:141], v[80:81], v[122:123], v[140:141]
	v_pk_fma_f32 v[142:143], v[182:183], v[132:133], v[142:143] op_sel:[1,0,0]
	v_pk_fma_f32 v[144:145], v[182:183], v[134:135], v[144:145] op_sel:[1,0,0]
	v_add_f32_e32 v148, v140, v141
	v_pk_mul_f32 v[146:147], v[116:117], v[82:83]
	ds_read_b128 v[100:103], v97 offset:5376
	v_add_f32_dpp v148, v148, v148 quad_perm:[1,0,3,2] row_mask:0xf bank_mask:0xf bound_ctrl:1
	v_pk_fma_f32 v[146:147], v[118:119], v[80:81], v[146:147]
	ds_read_b128 v[108:111], v97 offset:21760
	v_add_f32_dpp v148, v148, v148 quad_perm:[2,3,0,1] row_mask:0xf bank_mask:0xf bound_ctrl:1
	ds_read_b128 v[112:115], v97 offset:29952
	ds_read_b128 v[104:107], v97 offset:13568
	v_add_f32_dpp v148, v148, v148 row_ror:4 row_mask:0xf bank_mask:0xf bound_ctrl:1
	ds_read_b128 v[116:119], v97 offset:38144
	v_add_f32_e32 v206, v146, v147
	v_add_f32_dpp v148, v148, v148 row_ror:8 row_mask:0xf bank_mask:0xf bound_ctrl:1
	v_cndmask_b32_e64 v241, v194, v195, s[40:41]
	v_cndmask_b32_e64 v154, v197, v196, s[40:41]
	v_cndmask_b32_e64 v242, v196, v197, s[40:41]
	v_cndmask_b32_e64 v155, v199, v198, s[40:41]
	v_pk_fma_f32 v[82:83], v[124:125], v[148:149], v[142:143] op_sel_hi:[1,0,1]
	v_pk_fma_f32 v[80:81], v[126:127], v[148:149], v[144:145] op_sel_hi:[1,0,1]
	s_waitcnt lgkmcnt(6)
	v_pk_mul_f32 v[140:141], v[82:83], v[160:161]
	v_pk_mul_f32 v[142:143], v[82:83], v[168:169]
	v_pk_mul_f32 v[144:145], v[80:81], v[170:171]
	v_pk_fma_f32 v[140:141], v[80:81], v[162:163], v[140:141]
	s_waitcnt lgkmcnt(5)
	v_pk_fma_f32 v[142:143], v[184:185], v[172:173], v[142:143] op_sel_hi:[0,1,1]
	v_pk_fma_f32 v[144:145], v[184:185], v[174:175], v[144:145] op_sel_hi:[0,1,1]
	v_add_f32_e32 v148, v140, v141
	v_pk_mul_f32 v[146:147], v[136:137], v[82:83]
	ds_read_b128 v[120:123], v97 offset:5632
	v_add_f32_dpp v148, v148, v148 quad_perm:[1,0,3,2] row_mask:0xf bank_mask:0xf bound_ctrl:1
	v_pk_fma_f32 v[146:147], v[138:139], v[80:81], v[146:147]
	ds_read_b128 v[128:131], v97 offset:22016
	v_add_f32_dpp v148, v148, v148 quad_perm:[2,3,0,1] row_mask:0xf bank_mask:0xf bound_ctrl:1
	ds_read_b128 v[132:135], v97 offset:30208
	ds_read_b128 v[124:127], v97 offset:13824
	v_add_f32_dpp v148, v148, v148 row_ror:4 row_mask:0xf bank_mask:0xf bound_ctrl:1
	ds_read_b128 v[136:139], v97 offset:38400
	v_add_f32_e32 v207, v146, v147
	v_add_f32_dpp v148, v148, v148 row_ror:8 row_mask:0xf bank_mask:0xf bound_ctrl:1
	v_cndmask_b32_e64 v243, v198, v199, s[40:41]
	v_cndmask_b32_e64 v156, v201, v200, s[40:41]
	v_cndmask_b32_e64 v244, v200, v201, s[40:41]
	v_cndmask_b32_e64 v157, v203, v202, s[40:41]
	v_pk_fma_f32 v[82:83], v[164:165], v[148:149], v[142:143] op_sel_hi:[1,0,1]
	v_pk_fma_f32 v[80:81], v[166:167], v[148:149], v[144:145] op_sel_hi:[1,0,1]
	s_waitcnt lgkmcnt(5)
	v_pk_mul_f32 v[140:141], v[82:83], v[100:101]
	v_pk_mul_f32 v[142:143], v[82:83], v[108:109]
	v_pk_mul_f32 v[144:145], v[80:81], v[110:111]
	v_pk_fma_f32 v[140:141], v[80:81], v[102:103], v[140:141]
	v_pk_fma_f32 v[142:143], v[184:185], v[112:113], v[142:143] op_sel:[1,0,0]
	v_pk_fma_f32 v[144:145], v[184:185], v[114:115], v[144:145] op_sel:[1,0,0]
	v_add_f32_e32 v148, v140, v141
	v_pk_mul_f32 v[146:147], v[176:177], v[82:83]
	ds_read_b128 v[160:163], v97 offset:5888
	v_add_f32_dpp v148, v148, v148 quad_perm:[1,0,3,2] row_mask:0xf bank_mask:0xf bound_ctrl:1
	v_pk_fma_f32 v[146:147], v[178:179], v[80:81], v[146:147]
	ds_read_b128 v[168:171], v97 offset:22272
	v_add_f32_dpp v148, v148, v148 quad_perm:[2,3,0,1] row_mask:0xf bank_mask:0xf bound_ctrl:1
	ds_read_b128 v[172:175], v97 offset:30464
	ds_read_b128 v[164:167], v97 offset:14080
	v_add_f32_dpp v148, v148, v148 row_ror:4 row_mask:0xf bank_mask:0xf bound_ctrl:1
	ds_read_b128 v[176:179], v97 offset:38656
	v_add_f32_e32 v208, v146, v147
	v_add_f32_dpp v148, v148, v148 row_ror:8 row_mask:0xf bank_mask:0xf bound_ctrl:1
	v_cndmask_b32_e64 v245, v202, v203, s[40:41]
	v_add_f32_dpp v150, v238, v150 quad_perm:[1,0,3,2] row_mask:0xf bank_mask:0xf bound_ctrl:1
	v_add_f32_dpp v151, v239, v151 quad_perm:[1,0,3,2] row_mask:0xf bank_mask:0xf bound_ctrl:1
	v_add_f32_dpp v152, v240, v152 quad_perm:[1,0,3,2] row_mask:0xf bank_mask:0xf bound_ctrl:1
	v_pk_fma_f32 v[82:83], v[104:105], v[148:149], v[142:143] op_sel_hi:[1,0,1]
	v_pk_fma_f32 v[80:81], v[106:107], v[148:149], v[144:145] op_sel_hi:[1,0,1]
	s_waitcnt lgkmcnt(5)
	v_pk_mul_f32 v[140:141], v[82:83], v[120:121]
	v_pk_mul_f32 v[142:143], v[82:83], v[128:129]
	v_pk_mul_f32 v[144:145], v[80:81], v[130:131]
	v_pk_fma_f32 v[140:141], v[80:81], v[122:123], v[140:141]
	v_pk_fma_f32 v[142:143], v[186:187], v[132:133], v[142:143] op_sel_hi:[0,1,1]
	v_pk_fma_f32 v[144:145], v[186:187], v[134:135], v[144:145] op_sel_hi:[0,1,1]
	v_add_f32_e32 v148, v140, v141
	v_pk_mul_f32 v[146:147], v[116:117], v[82:83]
	ds_read_b128 v[100:103], v97 offset:6144
	v_add_f32_dpp v148, v148, v148 quad_perm:[1,0,3,2] row_mask:0xf bank_mask:0xf bound_ctrl:1
	v_pk_fma_f32 v[146:147], v[118:119], v[80:81], v[146:147]
	ds_read_b128 v[108:111], v97 offset:22528
	v_add_f32_dpp v148, v148, v148 quad_perm:[2,3,0,1] row_mask:0xf bank_mask:0xf bound_ctrl:1
	ds_read_b128 v[112:115], v97 offset:30720
	ds_read_b128 v[104:107], v97 offset:14336
	v_add_f32_dpp v148, v148, v148 row_ror:4 row_mask:0xf bank_mask:0xf bound_ctrl:1
	ds_read_b128 v[116:119], v97 offset:38912
	v_add_f32_e32 v209, v146, v147
	v_add_f32_dpp v148, v148, v148 row_ror:8 row_mask:0xf bank_mask:0xf bound_ctrl:1
	ds_read_b128 v[180:183], v1 offset:41056
	v_add_f32_dpp v153, v241, v153 quad_perm:[1,0,3,2] row_mask:0xf bank_mask:0xf bound_ctrl:1
	v_add_f32_dpp v154, v242, v154 quad_perm:[1,0,3,2] row_mask:0xf bank_mask:0xf bound_ctrl:1
	v_add_f32_dpp v155, v243, v155 quad_perm:[1,0,3,2] row_mask:0xf bank_mask:0xf bound_ctrl:1
	v_pk_fma_f32 v[82:83], v[124:125], v[148:149], v[142:143] op_sel_hi:[1,0,1]
	v_pk_fma_f32 v[80:81], v[126:127], v[148:149], v[144:145] op_sel_hi:[1,0,1]
	s_waitcnt lgkmcnt(6)
	v_pk_mul_f32 v[140:141], v[82:83], v[160:161]
	v_pk_mul_f32 v[142:143], v[82:83], v[168:169]
	v_pk_mul_f32 v[144:145], v[80:81], v[170:171]
	v_pk_fma_f32 v[140:141], v[80:81], v[162:163], v[140:141]
	v_pk_fma_f32 v[142:143], v[186:187], v[172:173], v[142:143] op_sel:[1,0,0]
	v_pk_fma_f32 v[144:145], v[186:187], v[174:175], v[144:145] op_sel:[1,0,0]
	v_add_f32_e32 v148, v140, v141
	v_pk_mul_f32 v[146:147], v[136:137], v[82:83]
	ds_read_b128 v[120:123], v97 offset:6400
	v_add_f32_dpp v148, v148, v148 quad_perm:[1,0,3,2] row_mask:0xf bank_mask:0xf bound_ctrl:1
	v_pk_fma_f32 v[146:147], v[138:139], v[80:81], v[146:147]
	ds_read_b128 v[128:131], v97 offset:22784
	v_add_f32_dpp v148, v148, v148 quad_perm:[2,3,0,1] row_mask:0xf bank_mask:0xf bound_ctrl:1
	ds_read_b128 v[132:135], v97 offset:30976
	ds_read_b128 v[124:127], v97 offset:14592
	v_add_f32_dpp v148, v148, v148 row_ror:4 row_mask:0xf bank_mask:0xf bound_ctrl:1
	ds_read_b128 v[136:139], v97 offset:39168
	v_add_f32_e32 v210, v146, v147
	v_add_f32_dpp v148, v148, v148 row_ror:8 row_mask:0xf bank_mask:0xf bound_ctrl:1
	v_add_f32_dpp v156, v244, v156 quad_perm:[1,0,3,2] row_mask:0xf bank_mask:0xf bound_ctrl:1
	v_add_f32_dpp v157, v245, v157 quad_perm:[1,0,3,2] row_mask:0xf bank_mask:0xf bound_ctrl:1
	v_cndmask_b32_e64 v238, v151, v150, s[42:43]
	v_cndmask_b32_e64 v242, v150, v151, s[42:43]
	v_pk_fma_f32 v[82:83], v[164:165], v[148:149], v[142:143] op_sel_hi:[1,0,1]
	v_pk_fma_f32 v[80:81], v[166:167], v[148:149], v[144:145] op_sel_hi:[1,0,1]
	s_waitcnt lgkmcnt(6)
	v_pk_mul_f32 v[140:141], v[82:83], v[100:101]
	v_pk_mul_f32 v[142:143], v[82:83], v[108:109]
	v_pk_mul_f32 v[144:145], v[80:81], v[110:111]
	v_pk_fma_f32 v[140:141], v[80:81], v[102:103], v[140:141]
	s_waitcnt lgkmcnt(5)
	v_pk_fma_f32 v[142:143], v[180:181], v[112:113], v[142:143] op_sel_hi:[0,1,1]
	v_pk_fma_f32 v[144:145], v[180:181], v[114:115], v[144:145] op_sel_hi:[0,1,1]
	v_add_f32_e32 v148, v140, v141
	v_pk_mul_f32 v[146:147], v[176:177], v[82:83]
	ds_read_b128 v[160:163], v97 offset:6656
	v_add_f32_dpp v148, v148, v148 quad_perm:[1,0,3,2] row_mask:0xf bank_mask:0xf bound_ctrl:1
	v_pk_fma_f32 v[146:147], v[178:179], v[80:81], v[146:147]
	ds_read_b128 v[168:171], v97 offset:23040
	v_add_f32_dpp v148, v148, v148 quad_perm:[2,3,0,1] row_mask:0xf bank_mask:0xf bound_ctrl:1
	ds_read_b128 v[172:175], v97 offset:31232
	ds_read_b128 v[164:167], v97 offset:14848
	v_add_f32_dpp v148, v148, v148 row_ror:4 row_mask:0xf bank_mask:0xf bound_ctrl:1
	ds_read_b128 v[176:179], v97 offset:39424
	v_add_f32_e32 v211, v146, v147
	v_add_f32_dpp v148, v148, v148 row_ror:8 row_mask:0xf bank_mask:0xf bound_ctrl:1
	v_cndmask_b32_e64 v239, v153, v152, s[42:43]
	v_cndmask_b32_e64 v243, v152, v153, s[42:43]
	v_cndmask_b32_e64 v240, v155, v154, s[42:43]
	v_cndmask_b32_e64 v244, v154, v155, s[42:43]
	v_pk_fma_f32 v[82:83], v[104:105], v[148:149], v[142:143] op_sel_hi:[1,0,1]
	v_pk_fma_f32 v[80:81], v[106:107], v[148:149], v[144:145] op_sel_hi:[1,0,1]
	s_waitcnt lgkmcnt(5)
	v_pk_mul_f32 v[140:141], v[82:83], v[120:121]
	v_pk_mul_f32 v[142:143], v[82:83], v[128:129]
	v_pk_mul_f32 v[144:145], v[80:81], v[130:131]
	v_pk_fma_f32 v[140:141], v[80:81], v[122:123], v[140:141]
	v_pk_fma_f32 v[142:143], v[180:181], v[132:133], v[142:143] op_sel:[1,0,0]
	v_pk_fma_f32 v[144:145], v[180:181], v[134:135], v[144:145] op_sel:[1,0,0]
	v_add_f32_e32 v148, v140, v141
	v_pk_mul_f32 v[146:147], v[116:117], v[82:83]
	ds_read_b128 v[100:103], v97 offset:6912
	v_add_f32_dpp v148, v148, v148 quad_perm:[1,0,3,2] row_mask:0xf bank_mask:0xf bound_ctrl:1
	v_pk_fma_f32 v[146:147], v[118:119], v[80:81], v[146:147]
	ds_read_b128 v[108:111], v97 offset:23296
	v_add_f32_dpp v148, v148, v148 quad_perm:[2,3,0,1] row_mask:0xf bank_mask:0xf bound_ctrl:1
	ds_read_b128 v[112:115], v97 offset:31488
	ds_read_b128 v[104:107], v97 offset:15104
	v_add_f32_dpp v148, v148, v148 row_ror:4 row_mask:0xf bank_mask:0xf bound_ctrl:1
	ds_read_b128 v[116:119], v97 offset:39680
	v_add_f32_e32 v212, v146, v147
	v_add_f32_dpp v148, v148, v148 row_ror:8 row_mask:0xf bank_mask:0xf bound_ctrl:1
	v_cndmask_b32_e64 v241, v157, v156, s[42:43]
	v_cndmask_b32_e64 v245, v156, v157, s[42:43]
	v_add_f32_dpp v238, v242, v238 quad_perm:[2,3,0,1] row_mask:0xf bank_mask:0xf bound_ctrl:1
	v_add_f32_dpp v239, v243, v239 quad_perm:[2,3,0,1] row_mask:0xf bank_mask:0xf bound_ctrl:1
	v_pk_fma_f32 v[82:83], v[124:125], v[148:149], v[142:143] op_sel_hi:[1,0,1]
	v_pk_fma_f32 v[80:81], v[126:127], v[148:149], v[144:145] op_sel_hi:[1,0,1]
	s_waitcnt lgkmcnt(5)
	v_pk_mul_f32 v[140:141], v[82:83], v[160:161]
	v_pk_mul_f32 v[142:143], v[82:83], v[168:169]
	v_pk_mul_f32 v[144:145], v[80:81], v[170:171]
	v_pk_fma_f32 v[140:141], v[80:81], v[162:163], v[140:141]
	v_pk_fma_f32 v[142:143], v[182:183], v[172:173], v[142:143] op_sel_hi:[0,1,1]
	v_pk_fma_f32 v[144:145], v[182:183], v[174:175], v[144:145] op_sel_hi:[0,1,1]
	v_add_f32_e32 v148, v140, v141
	v_pk_mul_f32 v[146:147], v[136:137], v[82:83]
	ds_read_b128 v[120:123], v97 offset:7168
	v_add_f32_dpp v148, v148, v148 quad_perm:[1,0,3,2] row_mask:0xf bank_mask:0xf bound_ctrl:1
	v_pk_fma_f32 v[146:147], v[138:139], v[80:81], v[146:147]
	ds_read_b128 v[128:131], v97 offset:23552
	v_add_f32_dpp v148, v148, v148 quad_perm:[2,3,0,1] row_mask:0xf bank_mask:0xf bound_ctrl:1
	ds_read_b128 v[132:135], v97 offset:31744
	ds_read_b128 v[124:127], v97 offset:15360
	v_add_f32_dpp v148, v148, v148 row_ror:4 row_mask:0xf bank_mask:0xf bound_ctrl:1
	ds_read_b128 v[136:139], v97 offset:39936
	v_add_f32_e32 v213, v146, v147
	v_add_f32_dpp v148, v148, v148 row_ror:8 row_mask:0xf bank_mask:0xf bound_ctrl:1
	ds_read_b128 v[184:187], v1 offset:41072
	v_add_f32_dpp v240, v244, v240 quad_perm:[2,3,0,1] row_mask:0xf bank_mask:0xf bound_ctrl:1
	v_add_f32_dpp v241, v245, v241 quad_perm:[2,3,0,1] row_mask:0xf bank_mask:0xf bound_ctrl:1
	v_cndmask_b32_e64 v150, v240, v238, s[44:45]
	v_pk_fma_f32 v[82:83], v[164:165], v[148:149], v[142:143] op_sel_hi:[1,0,1]
	v_pk_fma_f32 v[80:81], v[166:167], v[148:149], v[144:145] op_sel_hi:[1,0,1]
	s_waitcnt lgkmcnt(6)
	v_pk_mul_f32 v[140:141], v[82:83], v[100:101]
	v_pk_mul_f32 v[142:143], v[82:83], v[108:109]
	v_pk_mul_f32 v[144:145], v[80:81], v[110:111]
	v_pk_fma_f32 v[140:141], v[80:81], v[102:103], v[140:141]
	v_pk_fma_f32 v[142:143], v[182:183], v[112:113], v[142:143] op_sel:[1,0,0]
	v_pk_fma_f32 v[144:145], v[182:183], v[114:115], v[144:145] op_sel:[1,0,0]
	v_add_f32_e32 v148, v140, v141
	v_pk_mul_f32 v[146:147], v[176:177], v[82:83]
	ds_read_b128 v[160:163], v97 offset:7424
	v_add_f32_dpp v148, v148, v148 quad_perm:[1,0,3,2] row_mask:0xf bank_mask:0xf bound_ctrl:1
	v_pk_fma_f32 v[146:147], v[178:179], v[80:81], v[146:147]
	ds_read_b128 v[168:171], v97 offset:23808
	v_add_f32_dpp v148, v148, v148 quad_perm:[2,3,0,1] row_mask:0xf bank_mask:0xf bound_ctrl:1
	ds_read_b128 v[172:175], v97 offset:32000
	ds_read_b128 v[164:167], v97 offset:15616
	v_add_f32_dpp v148, v148, v148 row_ror:4 row_mask:0xf bank_mask:0xf bound_ctrl:1
	ds_read_b128 v[176:179], v97 offset:40192
	v_add_f32_e32 v214, v146, v147
	v_add_f32_dpp v148, v148, v148 row_ror:8 row_mask:0xf bank_mask:0xf bound_ctrl:1
	v_cndmask_b32_e64 v152, v238, v240, s[44:45]
	v_cndmask_b32_e64 v151, v241, v239, s[44:45]
	v_cndmask_b32_e64 v153, v239, v241, s[44:45]
	v_add_f32_dpp v150, v152, v150 row_ror:8 row_mask:0xf bank_mask:0xf bound_ctrl:1
	v_pk_fma_f32 v[82:83], v[104:105], v[148:149], v[142:143] op_sel_hi:[1,0,1]
	v_pk_fma_f32 v[80:81], v[106:107], v[148:149], v[144:145] op_sel_hi:[1,0,1]
	s_waitcnt lgkmcnt(6)
	v_pk_mul_f32 v[140:141], v[82:83], v[120:121]
	v_pk_mul_f32 v[142:143], v[82:83], v[128:129]
	v_pk_mul_f32 v[144:145], v[80:81], v[130:131]
	v_pk_fma_f32 v[140:141], v[80:81], v[122:123], v[140:141]
	s_waitcnt lgkmcnt(5)
	v_pk_fma_f32 v[142:143], v[184:185], v[132:133], v[142:143] op_sel_hi:[0,1,1]
	v_pk_fma_f32 v[144:145], v[184:185], v[134:135], v[144:145] op_sel_hi:[0,1,1]
	v_add_f32_e32 v148, v140, v141
	v_pk_mul_f32 v[146:147], v[116:117], v[82:83]
	ds_read_b128 v[100:103], v97 offset:7680
	v_add_f32_dpp v148, v148, v148 quad_perm:[1,0,3,2] row_mask:0xf bank_mask:0xf bound_ctrl:1
	v_pk_fma_f32 v[146:147], v[118:119], v[80:81], v[146:147]
	ds_read_b128 v[108:111], v97 offset:24064
	v_add_f32_dpp v148, v148, v148 quad_perm:[2,3,0,1] row_mask:0xf bank_mask:0xf bound_ctrl:1
	ds_read_b128 v[112:115], v97 offset:32256
	ds_read_b128 v[104:107], v97 offset:15872
	v_add_f32_dpp v148, v148, v148 row_ror:4 row_mask:0xf bank_mask:0xf bound_ctrl:1
	ds_read_b128 v[116:119], v97 offset:40448
	v_add_f32_e32 v215, v146, v147
	v_add_f32_dpp v148, v148, v148 row_ror:8 row_mask:0xf bank_mask:0xf bound_ctrl:1
	v_add_f32_dpp v151, v153, v151 row_ror:8 row_mask:0xf bank_mask:0xf bound_ctrl:1
	v_cndmask_b32_e64 v246, v151, v150, s[46:47]
	v_cndmask_b32_e64 v247, v150, v151, s[46:47]
	s_nop 1
	v_mov_b32_dpp v248, v247 row_ror:4 row_mask:0xf bank_mask:0xf bound_ctrl:1
	v_pk_fma_f32 v[82:83], v[124:125], v[148:149], v[142:143] op_sel_hi:[1,0,1]
	v_pk_fma_f32 v[80:81], v[126:127], v[148:149], v[144:145] op_sel_hi:[1,0,1]
	s_waitcnt lgkmcnt(5)
	v_pk_mul_f32 v[140:141], v[82:83], v[160:161]
	v_pk_mul_f32 v[142:143], v[82:83], v[168:169]
	v_pk_mul_f32 v[144:145], v[80:81], v[170:171]
	v_pk_fma_f32 v[140:141], v[80:81], v[162:163], v[140:141]
	v_pk_fma_f32 v[142:143], v[184:185], v[172:173], v[142:143] op_sel:[1,0,0]
	v_pk_fma_f32 v[144:145], v[184:185], v[174:175], v[144:145] op_sel:[1,0,0]
	v_add_f32_e32 v148, v140, v141
	v_pk_mul_f32 v[146:147], v[136:137], v[82:83]
	ds_read_b128 v[120:123], v97 offset:7936
	v_add_f32_dpp v148, v148, v148 quad_perm:[1,0,3,2] row_mask:0xf bank_mask:0xf bound_ctrl:1
	v_pk_fma_f32 v[146:147], v[138:139], v[80:81], v[146:147]
	ds_read_b128 v[128:131], v97 offset:24320
	v_add_f32_dpp v148, v148, v148 quad_perm:[2,3,0,1] row_mask:0xf bank_mask:0xf bound_ctrl:1
	ds_read_b128 v[132:135], v97 offset:32512
	ds_read_b128 v[124:127], v97 offset:16128
	v_add_f32_dpp v148, v148, v148 row_ror:4 row_mask:0xf bank_mask:0xf bound_ctrl:1
	ds_read_b128 v[136:139], v97 offset:40704
	v_add_f32_e32 v216, v146, v147
	v_add_f32_dpp v148, v148, v148 row_ror:8 row_mask:0xf bank_mask:0xf bound_ctrl:1
	v_mov_b32_dpp v249, v247 row_ror:12 row_mask:0xf bank_mask:0xf bound_ctrl:1
	v_cndmask_b32_e64 v249, v249, v248, s[38:39]
	v_add_f32_e32 v246, v246, v249
	ds_write_b32 v224, v246 offset:61952
	v_pk_fma_f32 v[82:83], v[164:165], v[148:149], v[142:143] op_sel_hi:[1,0,1]
	v_pk_fma_f32 v[80:81], v[166:167], v[148:149], v[144:145] op_sel_hi:[1,0,1]
	s_waitcnt lgkmcnt(6)
	v_pk_mul_f32 v[140:141], v[82:83], v[100:101]
	v_pk_mul_f32 v[142:143], v[82:83], v[108:109]
	v_pk_mul_f32 v[144:145], v[80:81], v[110:111]
	v_pk_fma_f32 v[140:141], v[80:81], v[102:103], v[140:141]
	v_pk_fma_f32 v[142:143], v[186:187], v[112:113], v[142:143] op_sel_hi:[0,1,1]
	v_pk_fma_f32 v[144:145], v[186:187], v[114:115], v[144:145] op_sel_hi:[0,1,1]
	v_add_f32_e32 v148, v140, v141
	v_pk_mul_f32 v[146:147], v[176:177], v[82:83]
	s_nop 0
	v_add_f32_dpp v148, v148, v148 quad_perm:[1,0,3,2] row_mask:0xf bank_mask:0xf bound_ctrl:1
	v_pk_fma_f32 v[146:147], v[178:179], v[80:81], v[146:147]
	s_nop 0
	v_add_f32_dpp v148, v148, v148 quad_perm:[2,3,0,1] row_mask:0xf bank_mask:0xf bound_ctrl:1
	s_nop 1
	v_add_f32_dpp v148, v148, v148 row_ror:4 row_mask:0xf bank_mask:0xf bound_ctrl:1
	v_add_f32_e32 v217, v146, v147
	s_nop 0
	v_add_f32_dpp v148, v148, v148 row_ror:8 row_mask:0xf bank_mask:0xf bound_ctrl:1
	v_pk_fma_f32 v[82:83], v[104:105], v[148:149], v[142:143] op_sel_hi:[1,0,1]
	v_pk_fma_f32 v[80:81], v[106:107], v[148:149], v[144:145] op_sel_hi:[1,0,1]
	s_waitcnt lgkmcnt(1)
	v_pk_mul_f32 v[140:141], v[82:83], v[120:121]
	v_pk_mul_f32 v[142:143], v[82:83], v[128:129]
	v_pk_mul_f32 v[144:145], v[80:81], v[130:131]
	v_pk_fma_f32 v[140:141], v[80:81], v[122:123], v[140:141]
	v_pk_fma_f32 v[142:143], v[186:187], v[132:133], v[142:143] op_sel:[1,0,0]
	v_pk_fma_f32 v[144:145], v[186:187], v[134:135], v[144:145] op_sel:[1,0,0]
	v_add_f32_e32 v148, v140, v141
	v_pk_mul_f32 v[146:147], v[116:117], v[82:83]
	s_nop 0
	v_add_f32_dpp v148, v148, v148 quad_perm:[1,0,3,2] row_mask:0xf bank_mask:0xf bound_ctrl:1
	v_pk_fma_f32 v[146:147], v[118:119], v[80:81], v[146:147]
	s_nop 0
	v_add_f32_dpp v148, v148, v148 quad_perm:[2,3,0,1] row_mask:0xf bank_mask:0xf bound_ctrl:1
	s_nop 1
	v_add_f32_dpp v148, v148, v148 row_ror:4 row_mask:0xf bank_mask:0xf bound_ctrl:1
	v_add_f32_e32 v218, v146, v147
	s_nop 0
	v_add_f32_dpp v148, v148, v148 row_ror:8 row_mask:0xf bank_mask:0xf bound_ctrl:1
	v_pk_fma_f32 v[82:83], v[124:125], v[148:149], v[142:143] op_sel_hi:[1,0,1]
	v_pk_fma_f32 v[80:81], v[126:127], v[148:149], v[144:145] op_sel_hi:[1,0,1]
	v_pk_mul_f32 v[146:147], v[136:137], v[82:83]
	v_pk_fma_f32 v[146:147], v[138:139], v[80:81], v[146:147]
	v_add_f32_e32 v219, v146, v147
	v_cndmask_b32_e64 v150, v205, v204, s[40:41]
	v_cndmask_b32_e64 v238, v204, v205, s[40:41]
	v_cndmask_b32_e64 v151, v207, v206, s[40:41]
	v_cndmask_b32_e64 v239, v206, v207, s[40:41]
	v_cndmask_b32_e64 v152, v209, v208, s[40:41]
	v_cndmask_b32_e64 v240, v208, v209, s[40:41]
	v_cndmask_b32_e64 v153, v211, v210, s[40:41]
	v_cndmask_b32_e64 v241, v210, v211, s[40:41]
	v_cndmask_b32_e64 v154, v213, v212, s[40:41]
	v_cndmask_b32_e64 v242, v212, v213, s[40:41]
	v_cndmask_b32_e64 v155, v215, v214, s[40:41]
	v_cndmask_b32_e64 v243, v214, v215, s[40:41]
	v_cndmask_b32_e64 v156, v217, v216, s[40:41]
	v_cndmask_b32_e64 v244, v216, v217, s[40:41]
	v_cndmask_b32_e64 v157, v219, v218, s[40:41]
	v_cndmask_b32_e64 v245, v218, v219, s[40:41]
	v_add_f32_dpp v150, v238, v150 quad_perm:[1,0,3,2] row_mask:0xf bank_mask:0xf bound_ctrl:1
	v_add_f32_dpp v151, v239, v151 quad_perm:[1,0,3,2] row_mask:0xf bank_mask:0xf bound_ctrl:1
	v_add_f32_dpp v152, v240, v152 quad_perm:[1,0,3,2] row_mask:0xf bank_mask:0xf bound_ctrl:1
	v_add_f32_dpp v153, v241, v153 quad_perm:[1,0,3,2] row_mask:0xf bank_mask:0xf bound_ctrl:1
	v_add_f32_dpp v154, v242, v154 quad_perm:[1,0,3,2] row_mask:0xf bank_mask:0xf bound_ctrl:1
	v_add_f32_dpp v155, v243, v155 quad_perm:[1,0,3,2] row_mask:0xf bank_mask:0xf bound_ctrl:1
	v_add_f32_dpp v156, v244, v156 quad_perm:[1,0,3,2] row_mask:0xf bank_mask:0xf bound_ctrl:1
	v_add_f32_dpp v157, v245, v157 quad_perm:[1,0,3,2] row_mask:0xf bank_mask:0xf bound_ctrl:1
	v_cndmask_b32_e64 v238, v151, v150, s[42:43]
	v_cndmask_b32_e64 v242, v150, v151, s[42:43]
	v_cndmask_b32_e64 v239, v153, v152, s[42:43]
	v_cndmask_b32_e64 v243, v152, v153, s[42:43]
	v_cndmask_b32_e64 v240, v155, v154, s[42:43]
	v_cndmask_b32_e64 v244, v154, v155, s[42:43]
	v_cndmask_b32_e64 v241, v157, v156, s[42:43]
	v_cndmask_b32_e64 v245, v156, v157, s[42:43]
	v_add_f32_dpp v238, v242, v238 quad_perm:[2,3,0,1] row_mask:0xf bank_mask:0xf bound_ctrl:1
	v_add_f32_dpp v239, v243, v239 quad_perm:[2,3,0,1] row_mask:0xf bank_mask:0xf bound_ctrl:1
	v_add_f32_dpp v240, v244, v240 quad_perm:[2,3,0,1] row_mask:0xf bank_mask:0xf bound_ctrl:1
	v_add_f32_dpp v241, v245, v241 quad_perm:[2,3,0,1] row_mask:0xf bank_mask:0xf bound_ctrl:1
	v_cndmask_b32_e64 v150, v240, v238, s[44:45]
	v_cndmask_b32_e64 v152, v238, v240, s[44:45]
	v_cndmask_b32_e64 v151, v241, v239, s[44:45]
	v_cndmask_b32_e64 v153, v239, v241, s[44:45]
	v_add_f32_dpp v150, v152, v150 row_ror:8 row_mask:0xf bank_mask:0xf bound_ctrl:1
	s_nop 0
	v_add_f32_dpp v151, v153, v151 row_ror:8 row_mask:0xf bank_mask:0xf bound_ctrl:1
	v_cndmask_b32_e64 v246, v151, v150, s[46:47]
	v_cndmask_b32_e64 v247, v150, v151, s[46:47]
	s_nop 1
	v_mov_b32_dpp v248, v247 row_ror:4 row_mask:0xf bank_mask:0xf bound_ctrl:1
	v_mov_b32_dpp v249, v247 row_ror:12 row_mask:0xf bank_mask:0xf bound_ctrl:1
	v_cndmask_b32_e64 v249, v249, v248, s[38:39]
	v_add_f32_e32 v246, v246, v249
	ds_write_b32 v224, v246 offset:62976
	v_mov_b64_e32 v[34:35], v[82:83]
	v_mov_b64_e32 v[36:37], v[80:81]
	s_branch .LBB0_484
